# dilated-pattern merge loop: the three pattern loads of an iteration are issued together with its lse loads (one memory round trip per iteration instead of two)
# speedup vs baseline: 1.0052x; 1.0003x over previous
.LBB0_1278:
	v_ashrrev_i32_e32 v0, 6, v2
	v_ashrrev_i32_e32 v1, 31, v0
	v_bfe_u32 v21, v2, 3, 3
	v_lshlrev_b64 v[4:5], 5, v[0:1]
	v_lshl_add_u64 v[4:5], s[14:15], 0, v[4:5]
	v_lshlrev_b32_e32 v64, 2, v21
	v_lshl_add_u64 v[4:5], v[4:5], 0, v[64:65]
	v_add_co_u32_e32 v6, vcc, 0x100000, v4
	global_load_dword v8, v[4:5], off
	s_nop 0
	v_addc_co_u32_e32 v7, vcc, 0, v5, vcc
	global_load_dword v6, v[6:7], off
	v_add_co_u32_e32 v4, vcc, 0x200000, v4
	v_and_b32_e32 v26, 56, v3
	s_nop 0
	v_addc_co_u32_e32 v5, vcc, 0, v5, vcc
	global_load_dword v4, v[4:5], off
	v_lshlrev_b64 v[40:41], 9, v[0:1]
	v_lshlrev_b32_e32 v46, 6, v21
	v_or3_b32 v40, v40, v46, v26
	v_lshlrev_b64 v[42:43], 1, v[40:41]
	v_lshl_add_u64 v[40:41], s[12:13], 0, v[42:43]
	v_lshl_add_u64 v[44:45], s[16:17], 0, v[42:43]
	global_load_dwordx4 v[28:31], v[40:41], off
	v_lshl_add_u64 v[42:43], s[18:19], 0, v[42:43]
	global_load_dwordx4 v[32:35], v[44:45], off
	global_load_dwordx4 v[36:39], v[42:43], off
	v_lshlrev_b32_e32 v64, 7, v21
	v_add_u32_e32 v2, s4, v2
	s_mov_b32 s1, 0x1fffff
	v_add_u32_e32 v3, s5, v3
	s_waitcnt vmcnt(3)
	v_max3_f32 v5, v8, v6, v4
	v_sub_f32_e32 v7, v8, v5
	v_sub_f32_e32 v6, v6, v5
	v_mul_f32_e32 v7, 0x3fb8aa3b, v7
	v_mul_f32_e32 v6, 0x3fb8aa3b, v6
	v_sub_f32_e32 v4, v4, v5
	v_exp_f32_e32 v17, v7
	v_exp_f32_e32 v16, v6
	v_mul_f32_e32 v4, 0x3fb8aa3b, v4
	v_exp_f32_e32 v4, v4
	v_add_f32_e32 v5, v17, v16
	v_add_f32_e32 v5, v4, v5
	v_div_scale_f32 v6, s[2:3], v5, v5, 1.0
	v_rcp_f32_e32 v7, v6
	s_nop 0
	v_fma_f32 v8, -v6, v7, 1.0
	v_fmac_f32_e32 v7, v8, v7
	v_div_scale_f32 v8, vcc, 1.0, v5, 1.0
	v_mul_f32_e32 v9, v8, v7
	v_fma_f32 v10, -v6, v9, v8
	v_fmac_f32_e32 v9, v10, v7
	v_fma_f32 v6, -v6, v9, v8
	v_div_fmas_f32 v6, v6, v7, v9
	v_div_fixup_f32 v18, v6, v5, 1.0
	v_mul_f32_e32 v20, v4, v18
	v_pk_mul_f32 v[16:17], v[16:17], v[18:19] op_sel_hi:[1,0]
	v_lshlrev_b64 v[0:1], 11, v[0:1]
	v_lshl_add_u64 v[0:1], s[8:9], 0, v[0:1]
	v_lshl_add_u64 v[0:1], v[0:1], 0, v[64:65]
	v_lshlrev_b32_e32 v64, 1, v26
	v_lshl_add_u64 v[0:1], v[0:1], 0, v[64:65]
	v_add_co_u32_e32 v0, vcc, 0x6d00000, v0
	s_waitcnt vmcnt(0)
	v_mov_b32_e32 v4, v28
	v_mov_b32_e32 v5, v29
	v_mov_b32_e32 v6, v30
	v_mov_b32_e32 v7, v31
	v_mov_b32_e32 v8, v32
	v_mov_b32_e32 v9, v33
	v_mov_b32_e32 v10, v34
	v_mov_b32_e32 v11, v35
	v_mov_b32_e32 v12, v36
	v_mov_b32_e32 v13, v37
	v_mov_b32_e32 v14, v38
	v_mov_b32_e32 v15, v39
	v_lshlrev_b32_e32 v22, 16, v4
	v_and_b32_e32 v19, 0xffff0000, v4
	v_and_b32_e32 v23, 0xffff0000, v8
	v_lshlrev_b32_e32 v18, 16, v8
	v_pk_mul_f32 v[22:23], v[16:17], v[22:23] op_sel:[1,0] op_sel_hi:[0,1]
	v_lshlrev_b32_e32 v24, 16, v12
	v_and_b32_e32 v25, 0xffff0000, v12
	v_pk_fma_f32 v[18:19], v[16:17], v[18:19], v[22:23]
	v_lshlrev_b32_e32 v8, 16, v5
	v_pk_fma_f32 v[18:19], v[20:21], v[24:25], v[18:19] op_sel_hi:[0,1,1]
	v_cvt_pk_bf16_f32 v4, v18, v19
	v_lshlrev_b32_e32 v18, 16, v9
	v_and_b32_e32 v9, 0xffff0000, v9
	v_and_b32_e32 v19, 0xffff0000, v5
	v_pk_mul_f32 v[8:9], v[16:17], v[8:9] op_sel:[1,0] op_sel_hi:[0,1]
	v_lshlrev_b32_e32 v12, 16, v13
	v_and_b32_e32 v13, 0xffff0000, v13
	v_pk_fma_f32 v[8:9], v[16:17], v[18:19], v[8:9]
	v_lshlrev_b32_e32 v18, 16, v14
	v_pk_fma_f32 v[8:9], v[20:21], v[12:13], v[8:9] op_sel_hi:[0,1,1]
	v_lshlrev_b32_e32 v12, 16, v6
	v_and_b32_e32 v13, 0xffff0000, v10
	v_cvt_pk_bf16_f32 v5, v8, v9
	v_lshlrev_b32_e32 v8, 16, v10
	v_and_b32_e32 v9, 0xffff0000, v6
	v_pk_mul_f32 v[12:13], v[16:17], v[12:13] op_sel:[1,0] op_sel_hi:[0,1]
	v_and_b32_e32 v19, 0xffff0000, v14
	v_pk_fma_f32 v[8:9], v[16:17], v[8:9], v[12:13]
	v_lshlrev_b32_e32 v10, 16, v7
	v_pk_fma_f32 v[8:9], v[20:21], v[18:19], v[8:9] op_sel_hi:[0,1,1]
	v_cvt_pk_bf16_f32 v6, v8, v9
	v_lshlrev_b32_e32 v8, 16, v11
	v_and_b32_e32 v11, 0xffff0000, v11
	v_and_b32_e32 v9, 0xffff0000, v7
	v_pk_mul_f32 v[10:11], v[16:17], v[10:11] op_sel:[1,0] op_sel_hi:[0,1]
	v_pk_fma_f32 v[8:9], v[16:17], v[8:9], v[10:11]
	v_lshlrev_b32_e32 v10, 16, v15
	v_and_b32_e32 v11, 0xffff0000, v15
	v_addc_co_u32_e32 v1, vcc, 0, v1, vcc
	v_pk_fma_f32 v[8:9], v[20:21], v[10:11], v[8:9] op_sel_hi:[0,1,1]
	v_cmp_lt_i32_e32 vcc, s1, v2
	v_cvt_pk_bf16_f32 v7, v8, v9
	s_or_b64 s[20:21], vcc, s[20:21]
	flat_store_dwordx4 v[0:1], v[4:7] offset:1024
	s_andn2_b64 exec, exec, s[20:21]
	s_cbranch_execnz .LBB0_1278
